# attention softmax max3 chain: six s_nop 0 between non-transcendental inline-asm v_max3_f32 removed (no ISA hazard there), on top of v97
# baseline (speedup 1.0000x reference)
.LBB0_466:
	v_max3_f32 v33, v96, v97, v80
	v_max3_f32 v34, v98, v99, v81
	s_mov_b32 s6, 0x40c00000
	v_max3_f32 v33, v33, v82, v83
	v_max3_f32 v34, v34, v102, v103
	v_lshl_add_u64 v[252:253], v[216:217], 0, s[66:67]
	global_load_dwordx4 v[164:167], v[252:253], off
	v_max3_f32 v33, v33, v100, v101
	v_max3_f32 v34, v34, v86, v87
	v_max3_f32 v33, v33, v84, v85
	v_max3_f32 v34, v34, v106, v107
	v_max3_f32 v33, v33, v104, v105
	v_max3_f32 v34, v34, v90, v91
	v_max3_f32 v33, v33, v88, v89
	v_max3_f32 v34, v34, v110, v111
	v_max3_f32 v33, v33, v108, v109
	v_max3_f32 v34, v34, v94, v95
	v_max3_f32 v33, v33, v92, v93
	v_max_f32_e32 v33, v33, v34
	v_mov_b32_e32 v34, v33
	s_nop 1
	v_permlane32_swap_b32_e32 v33, v34
	v_max_f32_e32 v33, v33, v34
	v_sub_f32_e32 v33, v33, v214
	v_cmp_lt_f32_e32 vcc, s6, v33
	s_or_b64 s[6:7], s[40:41], vcc
	s_cbranch_scc0 .LBB0_468
	v_max_f32_e32 v34, v33, v33
	v_max_f32_e32 v34, 0, v34
	v_cndmask_b32_e64 v33, v34, v33, s[40:41]
	v_exp_f32_e64 v34, -v33
	v_add_f32_e32 v214, v214, v33
	v_cndmask_b32_e64 v34, v34, 1.0, s[40:41]
	v_pk_mul_f32 v[78:79], v[78:79], v[34:35] op_sel_hi:[1,0]
	v_pk_mul_f32 v[76:77], v[76:77], v[34:35] op_sel_hi:[1,0]
	v_pk_mul_f32 v[74:75], v[74:75], v[34:35] op_sel_hi:[1,0]
	v_pk_mul_f32 v[72:73], v[72:73], v[34:35] op_sel_hi:[1,0]
	v_pk_mul_f32 v[70:71], v[70:71], v[34:35] op_sel_hi:[1,0]
	v_pk_mul_f32 v[68:69], v[68:69], v[34:35] op_sel_hi:[1,0]
	v_pk_mul_f32 v[66:67], v[66:67], v[34:35] op_sel_hi:[1,0]
	v_pk_mul_f32 v[64:65], v[64:65], v[34:35] op_sel_hi:[1,0]
	v_pk_mul_f32 v[62:63], v[62:63], v[34:35] op_sel_hi:[1,0]
	v_pk_mul_f32 v[60:61], v[60:61], v[34:35] op_sel_hi:[1,0]
	v_pk_mul_f32 v[58:59], v[58:59], v[34:35] op_sel_hi:[1,0]
	v_pk_mul_f32 v[56:57], v[56:57], v[34:35] op_sel_hi:[1,0]
	v_pk_mul_f32 v[54:55], v[54:55], v[34:35] op_sel_hi:[1,0]
	v_pk_mul_f32 v[52:53], v[52:53], v[34:35] op_sel_hi:[1,0]
	v_pk_mul_f32 v[50:51], v[50:51], v[34:35] op_sel_hi:[1,0]
	v_pk_mul_f32 v[48:49], v[48:49], v[34:35] op_sel_hi:[1,0]
	v_pk_mul_f32 v[30:31], v[30:31], v[34:35] op_sel_hi:[1,0]
	v_pk_mul_f32 v[28:29], v[28:29], v[34:35] op_sel_hi:[1,0]
	v_pk_mul_f32 v[26:27], v[26:27], v[34:35] op_sel_hi:[1,0]
	v_pk_mul_f32 v[24:25], v[24:25], v[34:35] op_sel_hi:[1,0]
	v_pk_mul_f32 v[22:23], v[22:23], v[34:35] op_sel_hi:[1,0]
	v_pk_mul_f32 v[20:21], v[20:21], v[34:35] op_sel_hi:[1,0]
	v_pk_mul_f32 v[18:19], v[18:19], v[34:35] op_sel_hi:[1,0]
	v_pk_mul_f32 v[16:17], v[16:17], v[34:35] op_sel_hi:[1,0]
	v_pk_mul_f32 v[14:15], v[14:15], v[34:35] op_sel_hi:[1,0]
	v_pk_mul_f32 v[12:13], v[12:13], v[34:35] op_sel_hi:[1,0]
	v_pk_mul_f32 v[10:11], v[10:11], v[34:35] op_sel_hi:[1,0]
	v_pk_mul_f32 v[8:9], v[8:9], v[34:35] op_sel_hi:[1,0]
	v_pk_mul_f32 v[6:7], v[6:7], v[34:35] op_sel_hi:[1,0]
	v_pk_mul_f32 v[4:5], v[4:5], v[34:35] op_sel_hi:[1,0]
	v_pk_mul_f32 v[2:3], v[2:3], v[34:35] op_sel_hi:[1,0]
	v_pk_mul_f32 v[0:1], v[0:1], v[34:35] op_sel_hi:[1,0]
	v_mul_f32_e32 v250, v250, v34
	s_mov_b64 s[40:41], 0
